# GLA prep stage-2 LDS reads batched (4 ds_read_b128 then one wait) on top of scan touch-prefetch
# speedup vs baseline: 1.0597x; 1.0009x over previous
.LBB0_758:
	v_add_u32_e32 v28, 0, v23
	v_add_u32_e32 v24, 0x18c00, v28
	v_add_u32_e32 v106, 0x18c10, v28
	v_add_u32_e32 v110, 0x18c20, v28
	v_add_u32_e32 v114, 0x18c30, v28
	ds_read_b128 v[24:27], v24
	ds_read_b128 v[106:109], v106
	ds_read_b128 v[110:113], v110
	ds_read_b128 v[114:117], v114
	v_add_u32_e32 v21, 1, v21
	v_cmp_ge_i32_e32 vcc, v21, v20
	v_add_u32_e32 v23, 64, v23
	s_or_b64 s[0:1], vcc, s[0:1]
	s_waitcnt vmcnt(0) lgkmcnt(0)
	v_fma_f32 v29, v7, v24, v19
	v_fmac_f32_e32 v29, v12, v25
	v_fmac_f32_e32 v29, v15, v26
	v_fmac_f32_e32 v29, v16, v27
	v_fmac_f32_e32 v29, v17, v106
	v_fmac_f32_e32 v29, v18, v107
	v_pk_mul_f32 v[24:25], v[0:1], v[108:109]
	s_nop 0
	v_add_f32_e32 v24, v29, v24
	v_add_f32_e32 v29, v24, v25
	v_pk_mul_f32 v[24:25], v[2:3], v[110:111]
	s_nop 0
	v_add_f32_e32 v24, v29, v24
	v_add_f32_e32 v29, v24, v25
	v_pk_mul_f32 v[24:25], v[4:5], v[112:113]
	s_nop 0
	v_add_f32_e32 v24, v29, v24
	v_add_f32_e32 v29, v24, v25
	v_pk_mul_f32 v[24:25], v[8:9], v[114:115]
	s_nop 0
	v_add_f32_e32 v24, v29, v24
	v_add_f32_e32 v28, v24, v25
	v_pk_mul_f32 v[24:25], v[10:11], v[116:117]
	s_nop 0
	v_add_f32_e32 v24, v28, v24
	v_add_f32_e32 v24, v24, v25
	v_min_f32_e32 v25, 0, v24
	v_mul_f32_e64 v24, |v24|, s56
	v_exp_f32_e32 v24, v24
	s_nop 0
	v_add_f32_e32 v24, 1.0, v24
	v_log_f32_e32 v24, v24
	s_nop 0
	v_fmac_f32_e32 v25, 0xbf317218, v24
	v_mul_f32_e32 v24, 0x3d800000, v25
	v_add_u32_e32 v25, 0, v22
	v_add_u32_e32 v22, 0x210, v22
	ds_write_b32 v25, v24
	s_andn2_b64 exec, exec, s[0:1]
	s_cbranch_execnz .LBB0_758
	s_or_b64 exec, exec, s[0:1]
	s_movk_i32 s0, 0x80
	v_cmp_gt_i32_e64 s[38:39], s0, v6
	s_waitcnt lgkmcnt(0)
	s_barrier
	s_and_saveexec_b64 s[0:1], s[38:39]
	s_cbranch_execz .LBB0_762
	v_lshl_add_u32 v0, v6, 2, 0
	v_mov_b32_e32 v1, 0
	s_mov_b32 s4, 0
